# mlstm2 P stage hand-written: gM / c values read once per lane, no per-element exec branches or dependent LDS reads
# speedup vs baseline: 1.0168x; 1.0168x over previous
; __device__ __forceinline__ u16 f2bf(float f) { return (u16)(pk2(f, 0.f) & 0xffffu); }
; __device__ void mlstm2_phase(const Params& p, unsigned char* smem) {
;     ...
; #pragma unroll
;               for (int n = 0; n < 8; ++n) if (n <= (wave | 1)) { const int s_ = 16 * n + l15; const float cs = gC2[s_];
; #pragma unroll
;                 for (int r = 0; r < 4; ++r) { const int t = 16 * wave + 4 * lq + r; const float val = (n <= wave && s_ <= t) ? accS[n][r] * __expf(cs - gM[t]) : 0.f; Ps[t * 136 + s_] = f2bf(val); } } }
.LBB0_445:
	ds_read_b32 v240, v154
	ds_read_b32 v241, v156
	ds_read_b32 v242, v158
	ds_read_b32 v243, v160
	ds_read_b32 v244, v152
	ds_read_b32 v245, v162
	v_bfe_u32 v254, v0, 4, 2
	v_and_b32_e32 v239, 15, v0
	v_lshlrev_b32_e32 v254, 2, v254
	v_sub_u32_e32 v254, v239, v254
	v_mov_b32_e32 v239, 0
	s_waitcnt lgkmcnt(0)
	s_and_b64 vcc, exec, s[86:87]
	s_cbranch_vccz .Lps_d0
	v_add_u32_e32 v248, v153, v155
	v_add_u32_e32 v249, v153, v157
	v_add_u32_e32 v255, v153, v159
	v_add_u32_e32 v98, v153, v161
	v_sub_f32_e32 v246, v244, v240
	v_sub_f32_e32 v247, v244, v241
	v_sub_f32_e32 v252, v244, v242
	v_sub_f32_e32 v253, v244, v243
	v_mul_f32_e32 v246, 0x3fb8aa3b, v246
	v_mul_f32_e32 v247, 0x3fb8aa3b, v247
	v_mul_f32_e32 v252, 0x3fb8aa3b, v252
	v_mul_f32_e32 v253, 0x3fb8aa3b, v253
	v_exp_f32_e32 v246, v246
	v_exp_f32_e32 v247, v247
	v_exp_f32_e32 v252, v252
	v_exp_f32_e32 v253, v253
	v_mul_f32_e32 v246, v86, v246
	v_mul_f32_e32 v247, v87, v247
	v_mul_f32_e32 v252, v88, v252
	v_mul_f32_e32 v253, v89, v253
	v_cvt_pk_bf16_f32 v246, v246, v93
	v_cvt_pk_bf16_f32 v247, v247, v93
	v_cvt_pk_bf16_f32 v252, v252, v93
	v_cvt_pk_bf16_f32 v253, v253, v93
	ds_write_b16 v248, v246
	ds_write_b16 v249, v247
	ds_write_b16 v255, v252
	ds_write_b16 v98, v253
	s_branch .Lps_e0
.Lps_d0:
	v_add_u32_e32 v248, v153, v155
	v_add_u32_e32 v249, v153, v157
	v_add_u32_e32 v255, v153, v159
	v_add_u32_e32 v98, v153, v161
	v_sub_f32_e32 v246, v244, v240
	v_sub_f32_e32 v247, v244, v241
	v_sub_f32_e32 v252, v244, v242
	v_sub_f32_e32 v253, v244, v243
	v_mul_f32_e32 v246, 0x3fb8aa3b, v246
	v_mul_f32_e32 v247, 0x3fb8aa3b, v247
	v_mul_f32_e32 v252, 0x3fb8aa3b, v252
	v_mul_f32_e32 v253, 0x3fb8aa3b, v253
	v_exp_f32_e32 v246, v246
	v_exp_f32_e32 v247, v247
	v_exp_f32_e32 v252, v252
	v_exp_f32_e32 v253, v253
	v_mul_f32_e32 v246, v86, v246
	v_mul_f32_e32 v247, v87, v247
	v_mul_f32_e32 v252, v88, v252
	v_mul_f32_e32 v253, v89, v253
	v_cmp_ge_i32_e32 vcc, 0, v254
	s_nop 1
	v_cndmask_b32_e32 v246, v239, v246, vcc
	v_cmp_ge_i32_e32 vcc, 1, v254
	s_nop 1
	v_cndmask_b32_e32 v247, v239, v247, vcc
	v_cmp_ge_i32_e32 vcc, 2, v254
	s_nop 1
	v_cndmask_b32_e32 v252, v239, v252, vcc
	v_cmp_ge_i32_e32 vcc, 3, v254
	s_nop 1
	v_cndmask_b32_e32 v253, v239, v253, vcc
	v_cvt_pk_bf16_f32 v246, v246, v93
	v_cvt_pk_bf16_f32 v247, v247, v93
	v_cvt_pk_bf16_f32 v252, v252, v93
	v_cvt_pk_bf16_f32 v253, v253, v93
	ds_write_b16 v248, v246
	ds_write_b16 v249, v247
	ds_write_b16 v255, v252
	ds_write_b16 v98, v253
.Lps_e0:
	s_and_b64 vcc, exec, s[96:97]
	s_cbranch_vccz .Lps_x1
	v_sub_f32_e32 v246, v245, v240
	v_sub_f32_e32 v247, v245, v241
	v_sub_f32_e32 v252, v245, v242
	v_sub_f32_e32 v253, v245, v243
	v_mul_f32_e32 v246, 0x3fb8aa3b, v246
	v_mul_f32_e32 v247, 0x3fb8aa3b, v247
	v_mul_f32_e32 v252, 0x3fb8aa3b, v252
	v_mul_f32_e32 v253, 0x3fb8aa3b, v253
	v_exp_f32_e32 v246, v246
	v_exp_f32_e32 v247, v247
	v_exp_f32_e32 v252, v252
	v_exp_f32_e32 v253, v253
	v_mul_f32_e32 v246, v82, v246
	v_mul_f32_e32 v247, v83, v247
	v_mul_f32_e32 v252, v84, v252
	v_mul_f32_e32 v253, v85, v253
	v_cvt_pk_bf16_f32 v246, v246, v93
	v_cvt_pk_bf16_f32 v247, v247, v93
	v_cvt_pk_bf16_f32 v252, v252, v93
	v_cvt_pk_bf16_f32 v253, v253, v93
	ds_write_b16 v163, v246
	ds_write_b16 v164, v247
	ds_write_b16 v165, v252
	ds_write_b16 v166, v253
	s_branch .Lps_e1
.Lps_x1:
	s_and_b64 vcc, exec, s[86:87]
	s_cbranch_vccz .Lps_z1
	v_sub_f32_e32 v246, v245, v240
	v_sub_f32_e32 v247, v245, v241
	v_sub_f32_e32 v252, v245, v242
	v_sub_f32_e32 v253, v245, v243
	v_mul_f32_e32 v246, 0x3fb8aa3b, v246
	v_mul_f32_e32 v247, 0x3fb8aa3b, v247
	v_mul_f32_e32 v252, 0x3fb8aa3b, v252
	v_mul_f32_e32 v253, 0x3fb8aa3b, v253
	v_exp_f32_e32 v246, v246
	v_exp_f32_e32 v247, v247
	v_exp_f32_e32 v252, v252
	v_exp_f32_e32 v253, v253
	v_mul_f32_e32 v246, v82, v246
	v_mul_f32_e32 v247, v83, v247
	v_mul_f32_e32 v252, v84, v252
	v_mul_f32_e32 v253, v85, v253
	v_cmp_ge_i32_e32 vcc, 0, v254
	s_nop 1
	v_cndmask_b32_e32 v246, v239, v246, vcc
	v_cmp_ge_i32_e32 vcc, 1, v254
	s_nop 1
	v_cndmask_b32_e32 v247, v239, v247, vcc
	v_cmp_ge_i32_e32 vcc, 2, v254
	s_nop 1
	v_cndmask_b32_e32 v252, v239, v252, vcc
	v_cmp_ge_i32_e32 vcc, 3, v254
	s_nop 1
	v_cndmask_b32_e32 v253, v239, v253, vcc
	v_cvt_pk_bf16_f32 v246, v246, v93
	v_cvt_pk_bf16_f32 v247, v247, v93
	v_cvt_pk_bf16_f32 v252, v252, v93
	v_cvt_pk_bf16_f32 v253, v253, v93
	ds_write_b16 v163, v246
	ds_write_b16 v164, v247
	ds_write_b16 v165, v252
	ds_write_b16 v166, v253
	s_branch .Lps_e1
.Lps_z1:
	ds_write_b16 v163, v239
	ds_write_b16 v164, v239
	ds_write_b16 v165, v239
	ds_write_b16 v166, v239
.Lps_e1:
	s_and_b64 vcc, exec, s[96:97]
	s_cbranch_vccz .LBB0_521
	ds_read_b32 v244, v167
	ds_read_b32 v245, v172
	s_waitcnt lgkmcnt(0)
	s_and_b64 vcc, exec, s[94:95]
	s_cbranch_vccz .Lps_d2
	v_sub_f32_e32 v246, v244, v240
	v_sub_f32_e32 v247, v244, v241
	v_sub_f32_e32 v252, v244, v242
	v_sub_f32_e32 v253, v244, v243
	v_mul_f32_e32 v246, 0x3fb8aa3b, v246
	v_mul_f32_e32 v247, 0x3fb8aa3b, v247
	v_mul_f32_e32 v252, 0x3fb8aa3b, v252
	v_mul_f32_e32 v253, 0x3fb8aa3b, v253
	v_exp_f32_e32 v246, v246
	v_exp_f32_e32 v247, v247
	v_exp_f32_e32 v252, v252
	v_exp_f32_e32 v253, v253
	v_mul_f32_e32 v246, v78, v246
	v_mul_f32_e32 v247, v79, v247
	v_mul_f32_e32 v252, v80, v252
	v_mul_f32_e32 v253, v81, v253
	v_cvt_pk_bf16_f32 v246, v246, v93
	v_cvt_pk_bf16_f32 v247, v247, v93
	v_cvt_pk_bf16_f32 v252, v252, v93
	v_cvt_pk_bf16_f32 v253, v253, v93
	ds_write_b16 v168, v246
	ds_write_b16 v169, v247
	ds_write_b16 v170, v252
	ds_write_b16 v171, v253
	s_branch .Lps_e2
; __device__ __forceinline__ u16 f2bf(float f) { return (u16)(pk2(f, 0.f) & 0xffffu); }
; __device__ void mlstm2_phase(const Params& p, unsigned char* smem) {
;     ...
; #pragma unroll
;               for (int n = 0; n < 8; ++n) if (n <= (wave | 1)) { const int s_ = 16 * n + l15; const float cs = gC2[s_];
; #pragma unroll
;                 for (int r = 0; r < 4; ++r) { const int t = 16 * wave + 4 * lq + r; const float val = (n <= wave && s_ <= t) ? accS[n][r] * __expf(cs - gM[t]) : 0.f; Ps[t * 136 + s_] = f2bf(val); } } }
.Lps_d2:
	v_sub_f32_e32 v246, v244, v240
	v_sub_f32_e32 v247, v244, v241
	v_sub_f32_e32 v252, v244, v242
	v_sub_f32_e32 v253, v244, v243
	v_mul_f32_e32 v246, 0x3fb8aa3b, v246
	v_mul_f32_e32 v247, 0x3fb8aa3b, v247
	v_mul_f32_e32 v252, 0x3fb8aa3b, v252
	v_mul_f32_e32 v253, 0x3fb8aa3b, v253
	v_exp_f32_e32 v246, v246
	v_exp_f32_e32 v247, v247
	v_exp_f32_e32 v252, v252
	v_exp_f32_e32 v253, v253
	v_mul_f32_e32 v246, v78, v246
	v_mul_f32_e32 v247, v79, v247
	v_mul_f32_e32 v252, v80, v252
	v_mul_f32_e32 v253, v81, v253
	v_cmp_ge_i32_e32 vcc, 0, v254
	s_nop 1
	v_cndmask_b32_e32 v246, v239, v246, vcc
	v_cmp_ge_i32_e32 vcc, 1, v254
	s_nop 1
	v_cndmask_b32_e32 v247, v239, v247, vcc
	v_cmp_ge_i32_e32 vcc, 2, v254
	s_nop 1
	v_cndmask_b32_e32 v252, v239, v252, vcc
	v_cmp_ge_i32_e32 vcc, 3, v254
	s_nop 1
	v_cndmask_b32_e32 v253, v239, v253, vcc
	v_cvt_pk_bf16_f32 v246, v246, v93
	v_cvt_pk_bf16_f32 v247, v247, v93
	v_cvt_pk_bf16_f32 v252, v252, v93
	v_cvt_pk_bf16_f32 v253, v253, v93
	ds_write_b16 v168, v246
	ds_write_b16 v169, v247
	ds_write_b16 v170, v252
	ds_write_b16 v171, v253
.Lps_e2:
	s_and_b64 vcc, exec, s[92:93]
	s_cbranch_vccz .Lps_x3
	v_sub_f32_e32 v246, v245, v240
	v_sub_f32_e32 v247, v245, v241
	v_sub_f32_e32 v252, v245, v242
	v_sub_f32_e32 v253, v245, v243
	v_mul_f32_e32 v246, 0x3fb8aa3b, v246
	v_mul_f32_e32 v247, 0x3fb8aa3b, v247
	v_mul_f32_e32 v252, 0x3fb8aa3b, v252
	v_mul_f32_e32 v253, 0x3fb8aa3b, v253
	v_exp_f32_e32 v246, v246
	v_exp_f32_e32 v247, v247
	v_exp_f32_e32 v252, v252
	v_exp_f32_e32 v253, v253
	v_mul_f32_e32 v246, v62, v246
	v_mul_f32_e32 v247, v63, v247
	v_mul_f32_e32 v252, v64, v252
	v_mul_f32_e32 v253, v65, v253
	v_cvt_pk_bf16_f32 v246, v246, v93
	v_cvt_pk_bf16_f32 v247, v247, v93
	v_cvt_pk_bf16_f32 v252, v252, v93
	v_cvt_pk_bf16_f32 v253, v253, v93
	ds_write_b16 v173, v246
	ds_write_b16 v174, v247
	ds_write_b16 v175, v252
	ds_write_b16 v176, v253
	s_branch .Lps_e3
.Lps_x3:
	s_and_b64 vcc, exec, s[94:95]
	s_cbranch_vccz .Lps_z3
	v_sub_f32_e32 v246, v245, v240
	v_sub_f32_e32 v247, v245, v241
	v_sub_f32_e32 v252, v245, v242
	v_sub_f32_e32 v253, v245, v243
	v_mul_f32_e32 v246, 0x3fb8aa3b, v246
	v_mul_f32_e32 v247, 0x3fb8aa3b, v247
	v_mul_f32_e32 v252, 0x3fb8aa3b, v252
	v_mul_f32_e32 v253, 0x3fb8aa3b, v253
	v_exp_f32_e32 v246, v246
	v_exp_f32_e32 v247, v247
	v_exp_f32_e32 v252, v252
	v_exp_f32_e32 v253, v253
	v_mul_f32_e32 v246, v62, v246
	v_mul_f32_e32 v247, v63, v247
	v_mul_f32_e32 v252, v64, v252
	v_mul_f32_e32 v253, v65, v253
	v_cmp_ge_i32_e32 vcc, 0, v254
	s_nop 1
	v_cndmask_b32_e32 v246, v239, v246, vcc
	v_cmp_ge_i32_e32 vcc, 1, v254
	s_nop 1
	v_cndmask_b32_e32 v247, v239, v247, vcc
	v_cmp_ge_i32_e32 vcc, 2, v254
	s_nop 1
	v_cndmask_b32_e32 v252, v239, v252, vcc
	v_cmp_ge_i32_e32 vcc, 3, v254
	s_nop 1
	v_cndmask_b32_e32 v253, v239, v253, vcc
	v_cvt_pk_bf16_f32 v246, v246, v93
	v_cvt_pk_bf16_f32 v247, v247, v93
	v_cvt_pk_bf16_f32 v252, v252, v93
	v_cvt_pk_bf16_f32 v253, v253, v93
	ds_write_b16 v173, v246
	ds_write_b16 v174, v247
	ds_write_b16 v175, v252
	ds_write_b16 v176, v253
	s_branch .Lps_e3
.Lps_z3:
	ds_write_b16 v173, v239
	ds_write_b16 v174, v239
	ds_write_b16 v175, v239
	ds_write_b16 v176, v239
.Lps_e3:
	s_and_b64 vcc, exec, s[92:93]
	s_cbranch_vccz .LBB0_521
	ds_read_b32 v244, v177
	ds_read_b32 v245, v182
	s_waitcnt lgkmcnt(0)
	s_and_b64 vcc, exec, s[62:63]
	s_cbranch_vccz .Lps_d4
	v_sub_f32_e32 v246, v244, v240
	v_sub_f32_e32 v247, v244, v241
	v_sub_f32_e32 v252, v244, v242
	v_sub_f32_e32 v253, v244, v243
	v_mul_f32_e32 v246, 0x3fb8aa3b, v246
	v_mul_f32_e32 v247, 0x3fb8aa3b, v247
	v_mul_f32_e32 v252, 0x3fb8aa3b, v252
	v_mul_f32_e32 v253, 0x3fb8aa3b, v253
	v_exp_f32_e32 v246, v246
	v_exp_f32_e32 v247, v247
	v_exp_f32_e32 v252, v252
	v_exp_f32_e32 v253, v253
	v_mul_f32_e32 v246, v74, v246
	v_mul_f32_e32 v247, v75, v247
	v_mul_f32_e32 v252, v76, v252
	v_mul_f32_e32 v253, v77, v253
	v_cvt_pk_bf16_f32 v246, v246, v93
	v_cvt_pk_bf16_f32 v247, v247, v93
	v_cvt_pk_bf16_f32 v252, v252, v93
	v_cvt_pk_bf16_f32 v253, v253, v93
	ds_write_b16 v178, v246
	ds_write_b16 v179, v247
	ds_write_b16 v180, v252
	ds_write_b16 v181, v253
	s_branch .Lps_e4
.Lps_d4:
	v_sub_f32_e32 v246, v244, v240
	v_sub_f32_e32 v247, v244, v241
	v_sub_f32_e32 v252, v244, v242
	v_sub_f32_e32 v253, v244, v243
	v_mul_f32_e32 v246, 0x3fb8aa3b, v246
	v_mul_f32_e32 v247, 0x3fb8aa3b, v247
	v_mul_f32_e32 v252, 0x3fb8aa3b, v252
	v_mul_f32_e32 v253, 0x3fb8aa3b, v253
	v_exp_f32_e32 v246, v246
	v_exp_f32_e32 v247, v247
	v_exp_f32_e32 v252, v252
	v_exp_f32_e32 v253, v253
	v_mul_f32_e32 v246, v74, v246
	v_mul_f32_e32 v247, v75, v247
	v_mul_f32_e32 v252, v76, v252
	v_mul_f32_e32 v253, v77, v253
	v_cmp_ge_i32_e32 vcc, 0, v254
	s_nop 1
	v_cndmask_b32_e32 v246, v239, v246, vcc
	v_cmp_ge_i32_e32 vcc, 1, v254
	s_nop 1
	v_cndmask_b32_e32 v247, v239, v247, vcc
	v_cmp_ge_i32_e32 vcc, 2, v254
	s_nop 1
	v_cndmask_b32_e32 v252, v239, v252, vcc
	v_cmp_ge_i32_e32 vcc, 3, v254
	s_nop 1
	v_cndmask_b32_e32 v253, v239, v253, vcc
	v_cvt_pk_bf16_f32 v246, v246, v93
	v_cvt_pk_bf16_f32 v247, v247, v93
	v_cvt_pk_bf16_f32 v252, v252, v93
	v_cvt_pk_bf16_f32 v253, v253, v93
	ds_write_b16 v178, v246
	ds_write_b16 v179, v247
	ds_write_b16 v180, v252
	ds_write_b16 v181, v253
; __device__ __forceinline__ u16 f2bf(float f) { return (u16)(pk2(f, 0.f) & 0xffffu); }
; #define MFMA16(a, b, c) __builtin_amdgcn_mfma_f32_16x16x32_bf16((a), (b), (c), 0, 0, 0)
; __device__ void mlstm2_phase(const Params& p, unsigned char* smem) {
;     ...
; #pragma unroll
;               for (int n = 0; n < 8; ++n) if (n <= (wave | 1)) { const int s_ = 16 * n + l15; const float cs = gC2[s_];
; #pragma unroll
;                 for (int r = 0; r < 4; ++r) { const int t = 16 * wave + 4 * lq + r; const float val = (n <= wave && s_ <= t) ? accS[n][r] * __expf(cs - gM[t]) : 0.f; Ps[t * 136 + s_] = f2bf(val); } } }
;             __syncthreads();
;             f32x4 oi[3], oc[3];
; #pragma unroll
;             for (int nt = 0; nt < 3; ++nt) { oi[nt] = (f32x4){0.f, 0.f, 0.f, 0.f}; oc[nt] = (f32x4){0.f, 0.f, 0.f, 0.f}; }
; #pragma unroll
;             for (int kk = 0; kk < 4; ++kk) if (kk <= (wave >> 1)) { const bf16x8 pf = *(const bf16x8*)(Ps + (16 * wave + l15) * 136 + 32 * kk + 8 * lq);
; #pragma unroll
;                 for (int nt = 0; nt < 3; ++nt) { const bf16x8 vf = *(const bf16x8*)(Vt + (16 * nt + l15) * 136 + 32 * kk + 8 * lq); oi[nt] = MFMA16(pf, vf, oi[nt]); } }
.Lps_e4:
	s_and_b64 vcc, exec, s[58:59]
	s_cbranch_vccz .Lps_x5
	v_sub_f32_e32 v246, v245, v240
	v_sub_f32_e32 v247, v245, v241
	v_sub_f32_e32 v252, v245, v242
	v_sub_f32_e32 v253, v245, v243
	v_mul_f32_e32 v246, 0x3fb8aa3b, v246
	v_mul_f32_e32 v247, 0x3fb8aa3b, v247
	v_mul_f32_e32 v252, 0x3fb8aa3b, v252
	v_mul_f32_e32 v253, 0x3fb8aa3b, v253
	v_exp_f32_e32 v246, v246
	v_exp_f32_e32 v247, v247
	v_exp_f32_e32 v252, v252
	v_exp_f32_e32 v253, v253
	v_mul_f32_e32 v246, v66, v246
	v_mul_f32_e32 v247, v67, v247
	v_mul_f32_e32 v252, v68, v252
	v_mul_f32_e32 v253, v69, v253
	v_cvt_pk_bf16_f32 v246, v246, v93
	v_cvt_pk_bf16_f32 v247, v247, v93
	v_cvt_pk_bf16_f32 v252, v252, v93
	v_cvt_pk_bf16_f32 v253, v253, v93
	ds_write_b16 v183, v246
	ds_write_b16 v184, v247
	ds_write_b16 v185, v252
	ds_write_b16 v186, v253
	s_branch .Lps_e5
.Lps_x5:
	s_and_b64 vcc, exec, s[62:63]
	s_cbranch_vccz .Lps_z5
	v_sub_f32_e32 v246, v245, v240
	v_sub_f32_e32 v247, v245, v241
	v_sub_f32_e32 v252, v245, v242
	v_sub_f32_e32 v253, v245, v243
	v_mul_f32_e32 v246, 0x3fb8aa3b, v246
	v_mul_f32_e32 v247, 0x3fb8aa3b, v247
	v_mul_f32_e32 v252, 0x3fb8aa3b, v252
	v_mul_f32_e32 v253, 0x3fb8aa3b, v253
	v_exp_f32_e32 v246, v246
	v_exp_f32_e32 v247, v247
	v_exp_f32_e32 v252, v252
	v_exp_f32_e32 v253, v253
	v_mul_f32_e32 v246, v66, v246
	v_mul_f32_e32 v247, v67, v247
	v_mul_f32_e32 v252, v68, v252
	v_mul_f32_e32 v253, v69, v253
	v_cmp_ge_i32_e32 vcc, 0, v254
	s_nop 1
	v_cndmask_b32_e32 v246, v239, v246, vcc
	v_cmp_ge_i32_e32 vcc, 1, v254
	s_nop 1
	v_cndmask_b32_e32 v247, v239, v247, vcc
	v_cmp_ge_i32_e32 vcc, 2, v254
	s_nop 1
	v_cndmask_b32_e32 v252, v239, v252, vcc
	v_cmp_ge_i32_e32 vcc, 3, v254
	s_nop 1
	v_cndmask_b32_e32 v253, v239, v253, vcc
	v_cvt_pk_bf16_f32 v246, v246, v93
	v_cvt_pk_bf16_f32 v247, v247, v93
	v_cvt_pk_bf16_f32 v252, v252, v93
	v_cvt_pk_bf16_f32 v253, v253, v93
	ds_write_b16 v183, v246
	ds_write_b16 v184, v247
	ds_write_b16 v185, v252
	ds_write_b16 v186, v253
	s_branch .Lps_e5
.Lps_z5:
	ds_write_b16 v183, v239
	ds_write_b16 v184, v239
	ds_write_b16 v185, v239
	ds_write_b16 v186, v239
.Lps_e5:
	s_and_b64 vcc, exec, s[58:59]
	s_cbranch_vccz .LBB0_521
	ds_read_b32 v244, v187
	ds_read_b32 v245, v192
	s_waitcnt lgkmcnt(0)
	s_and_b64 vcc, exec, s[60:61]
	s_cbranch_vccz .Lps_d6
	v_sub_f32_e32 v246, v244, v240
	v_sub_f32_e32 v247, v244, v241
	v_sub_f32_e32 v252, v244, v242
	v_sub_f32_e32 v253, v244, v243
	v_mul_f32_e32 v246, 0x3fb8aa3b, v246
	v_mul_f32_e32 v247, 0x3fb8aa3b, v247
	v_mul_f32_e32 v252, 0x3fb8aa3b, v252
	v_mul_f32_e32 v253, 0x3fb8aa3b, v253
	v_exp_f32_e32 v246, v246
	v_exp_f32_e32 v247, v247
	v_exp_f32_e32 v252, v252
	v_exp_f32_e32 v253, v253
	v_mul_f32_e32 v246, v70, v246
	v_mul_f32_e32 v247, v71, v247
	v_mul_f32_e32 v252, v72, v252
	v_mul_f32_e32 v253, v73, v253
	v_cvt_pk_bf16_f32 v246, v246, v93
	v_cvt_pk_bf16_f32 v247, v247, v93
	v_cvt_pk_bf16_f32 v252, v252, v93
	v_cvt_pk_bf16_f32 v253, v253, v93
	ds_write_b16 v188, v246
	ds_write_b16 v189, v247
	ds_write_b16 v190, v252
	ds_write_b16 v191, v253
	s_branch .Lps_e6
.Lps_d6:
	v_sub_f32_e32 v246, v244, v240
	v_sub_f32_e32 v247, v244, v241
	v_sub_f32_e32 v252, v244, v242
	v_sub_f32_e32 v253, v244, v243
	v_mul_f32_e32 v246, 0x3fb8aa3b, v246
	v_mul_f32_e32 v247, 0x3fb8aa3b, v247
	v_mul_f32_e32 v252, 0x3fb8aa3b, v252
	v_mul_f32_e32 v253, 0x3fb8aa3b, v253
	v_exp_f32_e32 v246, v246
	v_exp_f32_e32 v247, v247
	v_exp_f32_e32 v252, v252
	v_exp_f32_e32 v253, v253
	v_mul_f32_e32 v246, v70, v246
	v_mul_f32_e32 v247, v71, v247
	v_mul_f32_e32 v252, v72, v252
	v_mul_f32_e32 v253, v73, v253
	v_cmp_ge_i32_e32 vcc, 0, v254
	s_nop 1
	v_cndmask_b32_e32 v246, v239, v246, vcc
	v_cmp_ge_i32_e32 vcc, 1, v254
	s_nop 1
	v_cndmask_b32_e32 v247, v239, v247, vcc
	v_cmp_ge_i32_e32 vcc, 2, v254
	s_nop 1
	v_cndmask_b32_e32 v252, v239, v252, vcc
	v_cmp_ge_i32_e32 vcc, 3, v254
	s_nop 1
	v_cndmask_b32_e32 v253, v239, v253, vcc
	v_cvt_pk_bf16_f32 v246, v246, v93
	v_cvt_pk_bf16_f32 v247, v247, v93
	v_cvt_pk_bf16_f32 v252, v252, v93
	v_cvt_pk_bf16_f32 v253, v253, v93
	ds_write_b16 v188, v246
	ds_write_b16 v189, v247
	ds_write_b16 v190, v252
	ds_write_b16 v191, v253
.Lps_e6:
	s_and_b64 vcc, exec, s[60:61]
	s_cbranch_vccz .Lps_z7
	v_sub_f32_e32 v246, v245, v240
	v_sub_f32_e32 v247, v245, v241
	v_sub_f32_e32 v252, v245, v242
	v_sub_f32_e32 v253, v245, v243
	v_mul_f32_e32 v246, 0x3fb8aa3b, v246
	v_mul_f32_e32 v247, 0x3fb8aa3b, v247
	v_mul_f32_e32 v252, 0x3fb8aa3b, v252
	v_mul_f32_e32 v253, 0x3fb8aa3b, v253
	v_exp_f32_e32 v246, v246
	v_exp_f32_e32 v247, v247
	v_exp_f32_e32 v252, v252
	v_exp_f32_e32 v253, v253
	v_mul_f32_e32 v246, v58, v246
	v_mul_f32_e32 v247, v59, v247
	v_mul_f32_e32 v252, v60, v252
	v_mul_f32_e32 v253, v61, v253
	v_cmp_ge_i32_e32 vcc, 0, v254
	s_nop 1
	v_cndmask_b32_e32 v246, v239, v246, vcc
	v_cmp_ge_i32_e32 vcc, 1, v254
	s_nop 1
	v_cndmask_b32_e32 v247, v239, v247, vcc
	v_cmp_ge_i32_e32 vcc, 2, v254
	s_nop 1
	v_cndmask_b32_e32 v252, v239, v252, vcc
	v_cmp_ge_i32_e32 vcc, 3, v254
	s_nop 1
	v_cndmask_b32_e32 v253, v239, v253, vcc
	v_cvt_pk_bf16_f32 v246, v246, v93
	v_cvt_pk_bf16_f32 v247, v247, v93
	v_cvt_pk_bf16_f32 v252, v252, v93
	v_cvt_pk_bf16_f32 v253, v253, v93
	ds_write_b16 v193, v246
	ds_write_b16 v194, v247
	ds_write_b16 v195, v252
	ds_write_b16 v196, v253
	s_branch .Lps_e7
.Lps_z7:
	ds_write_b16 v193, v239
	ds_write_b16 v194, v239
	ds_write_b16 v195, v239
	ds_write_b16 v196, v239
.Lps_e7:
.LBB0_521:
	s_waitcnt lgkmcnt(0)
	s_barrier
	ds_read_b128 v[66:69], v123
	ds_read_b128 v[58:61], v229
	s_and_b64 vcc, exec, s[52:53]
	s_waitcnt lgkmcnt(0)
	v_mfma_f32_16x16x32_bf16 v[62:65], v[66:69], v[58:61], 0
	ds_read_b128 v[58:61], v229 offset:4352
	ds_read_b128 v[70:73], v229 offset:8704
	s_waitcnt lgkmcnt(1)
	v_mfma_f32_16x16x32_bf16 v[58:61], v[66:69], v[58:61], 0
	s_waitcnt lgkmcnt(0)
	v_mfma_f32_16x16x32_bf16 v[66:69], v[66:69], v[70:73], 0
	s_cbranch_vccz .LBB0_524
	s_and_b64 vcc, exec, s[54:55]
	s_cbranch_vccz .LBB0_525
